# cross-layer slot fusion: PEER retrieval of (layer0,pass1) now shares a slot with the in-proj of (layer1,pass0); layer-1 fp8 table conversion deferred to after that slot
# baseline (speedup 1.0000x reference)
; DEVI void phase_prep(const Params& P, int l, char* smem) {
;   const int tid = ltid();
;   char* ws = wsp(P, 0);
;   float* tile = reinterpret_cast<float*>(smem);
;   const int NT_WIN = 3072, NT_SQ = 256, NT_WQ = 512, NT_LRU = 64;
;   const int T0 = NT_WIN, T1 = T0 + 4 * NT_SQ, T2 = T1 + NT_WQ, T3 = T2 + NT_LRU;
;   const int C0 = T3 + 128, C1 = C0 + 4096, C2 = C1 + 4096;
;   const int X0 = C2;
;   const int L0 = X0 + (l == 0 ? 8 : 0);
;   for (int id = blockIdx.x; id < L0; id += gridDim.x) {
;     if (id < T0) {
;       int tr = id / 192, tc = id % 192;
;       transpose_tile(P.in[6] + (long)l * 1024 * 12288, (bfu*)(ws + O_WIN), 1024, 12288, tr * 64, tc * 64, tile, tid);
;     } else if (id < T1) {
;       int q = id - T0, w = q >> 8, t = q & 255;
;       const float* src = P.in[18 + w] + (long)l * 1048576;
;       bfu* dst = (bfu*)(ws + (w == 0 ? O_WOA : w == 1 ? O_WOB : w == 2 ? O_WOC : O_WO));
;       transpose_tile(src, dst, 1024, 1024, (t >> 4) * 64, (t & 15) * 64, tile, tid);
;     } else if (id < T2) {
;       int q = id - T1;
;       transpose_tile(P.in[24] + (long)l * 2097152, (bfu*)(ws + O_WQ), 1024, 2048, (q >> 5) * 64, (q & 31) * 64, tile, tid);
;     } else if (id < T3) {
;       int q = id - T2, mtx = q >> 2, t = q & 3, g = mtx >> 3, nb = mtx & 7;
;       const float* src = P.in[g == 0 ? 11 : 13] + (long)l * 131072 + nb * 16384;
;       transpose_tile(src, (bfu*)(ws + O_LRU) + mtx * 16384, 128, 128, (t >> 1) * 64, (t & 1) * 64, tile, tid);
;     } else if (id < C0) {
;       int q = id - T3;
;       convert_chunk(P.in[25] + (long)l * 262144 + (long)q * 2048, (bfu*)(ws + O_KEYS) + (long)q * 2048, tid);
;     } else if (id < C1) {
;       int q = id - C0;
;       convert_chunk_fp8(P.in[26] + (long)l * 16777216 + (long)q * 4096, (unsigned char*)(ws + O_UTB) + (long)q * 4096, U_SCALE, tid);
;     } else if (id < C2) {
;       int q = id - C1;
;       convert_chunk_fp8(P.in[27] + (long)l * 16777216 + (long)q * 4096, (unsigned char*)(ws + O_VTB) + (long)q * 4096, V_SCALE, tid);
;     } else {
;       int q = id - X0;
;       int c = (q & 3) * 256 + tid, ll = q >> 2;
;       float a0 = P.in[16][c], a1 = P.in[16][1024 + c];
;       float mx = fmaxf(a0, a1);
;       float e0 = __expf(a0 - mx), e1 = __expf(a1 - mx);
;       float p1 = e1 / (e0 + e1);
;       float* lbs = (float*)(ws + O_LBS);
;       lbs[ll * 1024 + c] = (ll == 0) ? 0.f : p1;
;     }
.LBB0_6:
	s_cmp_lg_u32 s0, 0
	s_cselect_b64 s[26:27], -1, 0
	s_cmp_eq_u32 s0, 0
	s_movk_i32 s1, 0x32c8
	s_cselect_b32 s2, s1, 0x12c0
	v_mov_b32_e32 v32, v93
	s_mov_b64 s[40:41], 0
	s_cmp_ge_i32 s74, s2
	s_cbranch_scc1 .LBB0_37
	v_lshlrev_b32_e32 v14, 4, v32
	v_lshlrev_b32_e32 v18, 3, v32
	v_lshl_add_u64 v[0:1], v[64:65], 0, s[40:41]
	v_ashrrev_i32_e32 v19, 31, v18
	s_mov_b64 s[42:43], 0x2480000
	v_lshlrev_b32_e32 v12, 2, v32
	v_and_b32_e32 v26, 48, v14
	s_ashr_i32 s1, s0, 31
	v_lshl_add_u64 v[8:9], v[18:19], 1, v[0:1]
	s_mov_b64 s[40:41], 0x2400000
	v_lshl_add_u64 v[10:11], v[0:1], 0, s[42:43]
	v_and_b32_e32 v24, 60, v12
	v_and_b32_e32 v12, -4, v32
	v_mul_u32_u24_e32 v13, 0x41, v26
	s_mov_b64 s[42:43], 0x2000000
	v_readlane_b32 s52, v253, 14
	s_lshl_b64 s[44:45], s[0:1], 26
	s_lshl_b64 s[46:47], s[0:1], 20
	v_lshl_add_u64 v[8:9], v[8:9], 0, s[40:41]
	s_lshl_b64 s[40:41], s[0:1], 19
	v_lshl_add_u32 v38, v13, 2, v12
	s_lshl_b64 s[48:49], s[0:1], 23
	v_lshl_add_u64 v[12:13], v[0:1], 0, s[42:43]
	s_lshl_b64 s[42:43], s[0:1], 22
	v_readlane_b32 s62, v253, 24
	v_readlane_b32 s63, v253, 25
	s_add_u32 s50, s62, s44
	v_readlane_b32 s60, v253, 22
	s_addc_u32 s51, s63, s45
	v_ashrrev_i32_e32 v15, 31, v14
	v_readlane_b32 s61, v253, 23
	s_add_u32 s44, s60, s44
	s_mov_b64 s[4:5], 0x6500000
	v_readlane_b32 s58, v253, 20
	v_lshlrev_b64 v[16:17], 2, v[14:15]
	s_addc_u32 s45, s61, s45
	v_lshl_add_u64 v[2:3], v[0:1], 0, s[4:5]
	v_lshl_add_u64 v[6:7], v[0:1], 0, v[14:15]
	s_mov_b64 s[4:5], 0x4500000
	v_readlane_b32 s59, v253, 21
	v_lshl_add_u64 v[14:15], s[50:51], 0, v[16:17]
	v_lshl_add_u64 v[16:17], s[44:45], 0, v[16:17]
	s_add_u32 s44, s58, s46
	v_lshl_add_u64 v[4:5], v[6:7], 0, s[4:5]
	s_mov_b64 s[4:5], 0x2500000
	v_readlane_b32 s56, v253, 18
	s_addc_u32 s45, s59, s47
	v_lshl_add_u64 v[6:7], v[6:7], 0, s[4:5]
	v_ashrrev_i32_e32 v33, 4, v32
	s_movk_i32 s24, 0x104
	v_readlane_b32 s57, v253, 19
	v_lshl_add_u64 v[18:19], v[18:19], 2, s[44:45]
	s_add_u32 s44, s56, s48
	v_readlane_b32 s4, v254, 44
	v_lshlrev_b32_e32 v88, 2, v24
	v_mul_lo_u32 v25, v33, s24
	s_mul_i32 s24, s0, 0x3000000
	s_addc_u32 s45, s57, s49
	v_readlane_b32 s12, v254, 52
	s_mul_hi_i32 s1, s0, 0x3000000
	v_lshl_add_u64 v[20:21], s[44:45], 0, v[88:89]
	v_readlane_b32 s13, v254, 53
	s_add_u32 s44, s12, s24
	s_addc_u32 s45, s13, s1
	v_add_u32_e32 v39, v88, v25
	v_add_u32_e32 v34, 16, v33
	v_add_u32_e32 v35, 32, v33
	v_add_u32_e32 v36, 48, v33
	v_ashrrev_i32_e32 v37, 2, v32
	v_lshl_add_u64 v[22:23], s[44:45], 0, v[88:89]
	v_add_u32_e32 v40, 0x1040, v39
	v_add_u32_e32 v41, 0x1048, v39
	v_add_u32_e32 v42, 0x2080, v39
	v_add_u32_e32 v43, 0x2088, v39
	v_add_u32_e32 v44, 0x30c0, v39
	v_add_u32_e32 v45, 0x30c8, v39
	v_lshlrev_b32_e32 v24, 2, v24
	v_add_u32_e32 v46, 0x400, v38
	v_add_u32_e32 v47, 0x800, v38
	v_add_u32_e32 v48, 0xc00, v38
	v_lshlrev_b32_e32 v88, 1, v26
	v_readlane_b32 s1, v252, 24
	v_readlane_b32 s46, v252, 22
	v_readlane_b32 s47, v252, 20
	v_readlane_b32 s48, v252, 18
	v_readlane_b32 s49, v252, 16
	v_readlane_b32 s50, v252, 14
	s_mov_b32 s51, s74
	v_readlane_b32 s53, v253, 15
	v_readlane_b32 s54, v253, 16
	v_readlane_b32 s55, v253, 17
	v_readlane_b32 s64, v253, 26
	v_readlane_b32 s65, v253, 27
	v_readlane_b32 s66, v253, 28
	v_readlane_b32 s67, v253, 29
	v_readlane_b32 s5, v254, 45
	v_readlane_b32 s6, v254, 46
	v_readlane_b32 s7, v254, 47
	v_readlane_b32 s8, v254, 48
	v_readlane_b32 s9, v254, 49
	v_readlane_b32 s10, v254, 50
	v_readlane_b32 s11, v254, 51
	v_readlane_b32 s14, v254, 54
	v_readlane_b32 s15, v254, 55
	v_readlane_b32 s16, v254, 56
	v_readlane_b32 s17, v254, 57
	v_readlane_b32 s18, v254, 58
	v_readlane_b32 s19, v254, 59
	s_branch .LBB0_9

; #define LND asm volatile("" : "+s"(l), "+s"(pass))
; #define GSYNC xcd_barrier(bar, xcc, nloc, nx)
; __global__ void __launch_bounds__(256, 2) fwd_megakernel(Params P) {
;     ...
;     const int role = ROLE_SPLIT ? ((blockIdx.x >> 8) & 1) : ROLE_ALL;
; #pragma unroll 1
;     for (int it = 0; it < 3; ++it) {
; #pragma unroll 1
;       for (int step = 0; step < 2; ++step) {
;         int pass;
;         if ((step ^ role) == 0) {
;           if (it < 2) { pass = __builtin_amdgcn_readfirstlane(it); LND; phase_inproj(P, l, pass, smem); }
;         } else {
;           if (it > 0) { pass = __builtin_amdgcn_readfirstlane(it - 1); LND; phase11(P, l, pass, smem); }
;         }
;       }
;       if (!(l == 1 && it == 2)) GSYNC;
.LBB0_123:
	s_lshl_b32 vcc_lo, s0, 2
	s_or_b32 vcc_lo, vcc_lo, s51
	s_lshr_b32 vcc_lo, 0x72, vcc_lo
	s_bitcmp1_b32 vcc_lo, 0
	s_cselect_b64 s[26:27], -1, 0
	v_writelane_b32 v252, s0, 60
	s_cmp_eq_u32 s51, 2
	s_cselect_b64 s[4:5], -1, 0
	v_writelane_b32 v252, s4, 34
	s_cmp_lg_u32 s51, 2
	s_cselect_b64 s[6:7], -1, 0
	v_writelane_b32 v252, s5, 35
	v_writelane_b32 v252, s51, 36
	s_mov_b64 s[72:73], -1
	s_mov_b32 s2, s0
	v_writelane_b32 v252, s6, 37
	s_nop 1
	v_writelane_b32 v252, s7, 38
	s_mov_b64 s[40:41], -1
	s_getreg_b32 vcc_lo, hwreg(HW_REG_XCC_ID, 0, 4)
	s_nop 1
	s_bitcmp1_b32 vcc_lo, 0
	s_cbranch_scc1 .LBB0_277
	s_branch .LBB0_125
.Lsplit_latch:
	s_getreg_b32 vcc_lo, hwreg(HW_REG_XCC_ID, 0, 4)
	s_nop 1
	s_bitcmp1_b32 vcc_lo, 0
	s_cbranch_scc0 .LBB0_124
	s_waitcnt vmcnt(0) lgkmcnt(0)
	s_barrier
	v_readlane_b32 s51, v252, 36
	s_mov_b32 s2, s0
	s_nop 1
	s_lshl_b32 vcc_lo, s0, 2
	s_or_b32 vcc_lo, vcc_lo, s51
	s_lshr_b32 vcc_lo, 0x72, vcc_lo
	s_bitcmp1_b32 vcc_lo, 0
	s_cselect_b64 s[26:27], -1, 0
	s_branch .LBB0_125

; DEVI int ltid() { int t = threadIdx.x; asm volatile("" : "+v"(t)); return t; }
; #define LND asm volatile("" : "+s"(l), "+s"(pass))
; DEVI void phase11(const Params& P, int l, int pass, char* smem) {
;   const int ntok = pass ? 8192 : 8448, base = pass ? 8448 : 0;
;   const int tid = ltid(); const int w = tid >> 6, lane = tid & 63;
;   float* scl = (float*)smem;
;   float* sv = scl + 2048;
;   int* si = (int*)(sv + 256);
;   float* tops = (float*)(si + 256);
;   int* tope = (int*)(tops + 128);
;   float* wgt = (float*)(tope + 128);
;   float* svs = wgt + 128;
;   int* sis = (int*)(svs + 256);
;   float* red = (float*)(sis + 256);
;   float* stat = red + 4096;
;   const float* SC = (const float*)(P.ws + O_AU);
;   const unsigned char* UT = (const unsigned char*)(P.ws + O_UTB);
;   const unsigned char* VTb = (const unsigned char*)(P.ws + O_VTB);
;   const float* g2 = P.in[28] + l * 1024;
;   const float* b2 = P.in[29] + l * 1024;
;   bfu* xb = (bfu*)(P.ws + O_XB);
;   const unsigned long long ltmask = (1ull << lane) - 1ull;
;   for (int lt = blockIdx.x; lt < ntok; lt += gridDim.x) {
;     const int it = base + lt;
; __global__ void __launch_bounds__(256, 2) fwd_megakernel(Params P) {
;     ...
;           if (it > 0) { pass = __builtin_amdgcn_readfirstlane(it - 1); LND; phase11(P, l, pass, smem); }
.LBB0_125:
	s_andn2_b64 vcc, exec, s[26:27]
	s_mov_b32 s0, s2
	s_cbranch_vccnz .LBB0_276
	s_add_i32 s1, s51, -1
	s_mov_b32 s0, s2
	s_cmp_eq_u32 s51, 0
	s_cselect_b32 s1, 1, s1
	s_cselect_b32 s0, 0, s0
	s_cmp_eq_u32 s1, 0
	s_cselect_b64 s[40:41], -1, 0
	s_and_b64 s[42:43], s[40:41], exec
	s_movk_i32 s1, 0x2100
	s_cselect_b32 s1, s1, 0x2000
	v_readlane_b32 s58, v252, 32
	v_mov_b32_e32 v0, v93
	s_cmp_ge_i32 s58, s1
	s_cbranch_scc1 .LBB0_276
	v_and_b32_e32 v88, 63, v0
	v_lshlrev_b64 v[2:3], v0, -1
	v_not_b32_e32 v91, v3
	v_not_b32_e32 v100, v2
	v_lshlrev_b32_e32 v2, 4, v88
	v_mov_b32_e32 v3, v89
	v_lshl_add_u64 v[110:111], v[70:71], 0, v[2:3]
	v_lshl_add_u64 v[112:113], v[68:69], 0, v[2:3]
	v_and_b32_e32 v3, 32, v0
	v_and_b32_e32 v4, 64, v187
	v_cmp_eq_u32_e64 s[44:45], 0, v3
	v_xor_b32_e32 v3, 32, v187
	v_add_u32_e32 v4, 64, v4
	v_cmp_lt_i32_e32 vcc, v3, v4
	v_and_b32_e32 v7, 15, v0
	s_and_b64 s[40:41], s[40:41], exec
	v_cndmask_b32_e32 v3, v187, v3, vcc
	v_lshlrev_b32_e32 v125, 2, v3
	v_and_b32_e32 v3, 16, v0
	v_cmp_eq_u32_e64 s[46:47], 0, v3
	v_xor_b32_e32 v3, 16, v187
	v_cmp_lt_i32_e32 vcc, v3, v4
	s_cselect_b32 s82, 0, 0x2100
	s_lshl_b32 s40, s0, 10
	v_cndmask_b32_e32 v3, v187, v3, vcc
	v_lshlrev_b32_e32 v126, 2, v3
	v_and_b32_e32 v3, 8, v0
	v_cmp_eq_u32_e64 s[48:49], 0, v3
	v_xor_b32_e32 v3, 8, v187
	v_cmp_lt_i32_e32 vcc, v3, v4
	s_ashr_i32 s41, s40, 31
	v_readlane_b32 s4, v253, 14
	v_cndmask_b32_e32 v3, v187, v3, vcc
	v_lshlrev_b32_e32 v127, 2, v3
	v_xor_b32_e32 v3, 4, v187
	v_cmp_lt_i32_e32 vcc, v3, v4
	s_lshl_b64 s[40:41], s[40:41], 2
	v_readlane_b32 s18, v253, 28
	v_cndmask_b32_e32 v3, v187, v3, vcc
	v_lshlrev_b32_e32 v128, 2, v3
	v_xor_b32_e32 v3, 2, v187
	v_cmp_lt_i32_e32 vcc, v3, v4
	v_readlane_b32 s19, v253, 29
	s_add_u32 s54, s18, s40
	v_cndmask_b32_e32 v3, v187, v3, vcc
	v_lshlrev_b32_e32 v129, 2, v3
	v_xor_b32_e32 v3, 1, v187
	v_cmp_lt_i32_e32 vcc, v3, v4
	v_readlane_b32 s16, v253, 26
	s_addc_u32 s55, s19, s41
	v_cndmask_b32_e32 v3, v187, v3, vcc
	v_cmp_ne_u32_e32 vcc, 0, v7
	v_readlane_b32 s17, v253, 27
	s_add_u32 s56, s16, s40
	v_cndmask_b32_e64 v132, 0, 1, vcc
	v_cmp_lt_u32_e32 vcc, 1, v7
	v_ashrrev_i32_e32 v6, 6, v0
	s_addc_u32 s57, s17, s41
	v_cndmask_b32_e64 v133, 0, 1, vcc
	v_cmp_lt_u32_e32 vcc, 2, v7
	v_and_b32_e32 v109, 0xffffffc0, v0
	v_lshlrev_b32_e32 v104, 2, v0
	v_cndmask_b32_e64 v134, 0, 1, vcc
	v_cmp_lt_u32_e32 vcc, 3, v7
	v_lshlrev_b32_e32 v108, 7, v6
	s_movk_i32 s24, 0xf80
	v_cndmask_b32_e64 v135, 0, 1, vcc
	v_cmp_lt_u32_e32 vcc, 4, v7
	v_readlane_b32 s6, v253, 16
	v_readlane_b32 s7, v253, 17
	v_cndmask_b32_e64 v136, 0, 1, vcc
	v_cmp_lt_u32_e32 vcc, 5, v7
	v_ashrrev_i32_e32 v1, 31, v0
	v_lshlrev_b32_e32 v101, 3, v0
	v_cndmask_b32_e64 v137, 0, 1, vcc
	v_cmp_lt_u32_e32 vcc, 6, v7
	s_getpc_b64 s[42:43]
	s_add_u32 s42, s42, CAND_IJ@rel32@lo+4
	s_addc_u32 s43, s43, CAND_IJ@rel32@hi+12
	v_cndmask_b32_e64 v138, 0, 1, vcc
	v_cmp_lt_u32_e32 vcc, 7, v7
	s_movk_i32 s4, 0x80
	v_lshlrev_b32_e32 v130, 2, v3
	v_cndmask_b32_e64 v139, 0, 1, vcc
	v_cmp_lt_u32_e32 vcc, 8, v7
	v_and_b32_e32 v3, 7, v0
	v_mad_u64_u32 v[4:5], s[52:53], v6, s24, v[108:109]
	v_cndmask_b32_e64 v140, 0, 1, vcc
	v_cmp_lt_u32_e32 vcc, 9, v7
	v_ashrrev_i32_e32 v105, 31, v104
	s_movk_i32 s24, 0xf004
	v_cndmask_b32_e64 v141, 0, 1, vcc
	v_cmp_lt_u32_e32 vcc, 10, v7
	v_readlane_b32 s6, v252, 37
	v_lshlrev_b32_e32 v8, 2, v88
	v_cndmask_b32_e64 v142, 0, 1, vcc
	v_cmp_lt_u32_e32 vcc, 11, v7
	v_lshl_add_u64 v[102:103], v[0:1], 3, v[72:73]
	v_lshlrev_b32_e32 v1, 11, v6
	v_cndmask_b32_e64 v143, 0, 1, vcc
	v_cmp_lt_u32_e32 vcc, 12, v7
	v_and_b32_e32 v121, -16, v0
	v_sub_u32_e32 v122, v101, v104
	v_cndmask_b32_e64 v144, 0, 1, vcc
	v_cmp_lt_u32_e32 vcc, 13, v7
	v_lshl_add_u64 v[106:107], s[42:43], 0, v[88:89]
	v_lshlrev_b32_e32 v124, 5, v6
	v_cmp_gt_u32_e64 s[42:43], 32, v88
	v_cmp_eq_u32_e64 s[50:51], 0, v3
	v_mul_lo_u32 v3, v0, 12
	v_mul_lo_u32 v5, v6, s24
	v_cndmask_b32_e64 v145, 0, 1, vcc
	v_cmp_eq_u32_e32 vcc, 15, v7
	v_lshlrev_b64 v[6:7], 2, v[104:105]
	v_lshrrev_b32_e32 v0, 1, v0
	v_readlane_b32 s7, v252, 38
	v_readlane_b32 s23, v252, 31
	v_or_b32_e32 v120, 64, v88
	v_lshlrev_b32_e32 v123, 2, v121
	v_cmp_gt_u32_e64 s[40:41], 50, v88
	v_lshl_add_u32 v131, v88, 6, v4
	v_cmp_eq_u32_e64 s[52:53], 0, v88
	v_lshl_add_u64 v[114:115], v[104:105], 1, v[66:67]
	v_cndmask_b32_e64 v146, 0, 1, vcc
	v_lshl_add_u64 v[116:117], s[56:57], 0, v[6:7]
	v_lshl_add_u64 v[118:119], s[54:55], 0, v[6:7]
	v_add_u32_e32 v147, 0x2800, v108
	v_and_b32_e32 v148, 28, v0
	v_add_u32_e32 v149, v8, v1
	v_lshlrev_b32_e32 v150, 2, v2
	v_add_u32_e32 v151, v122, v3
	v_add_u32_e32 v152, v4, v5
	s_mov_b32 s74, s58
	v_readlane_b32 s5, v253, 15
	v_readlane_b32 s8, v253, 18
	v_readlane_b32 s9, v253, 19
	v_readlane_b32 s10, v253, 20
	v_readlane_b32 s11, v253, 21
	v_readlane_b32 s12, v253, 22
	v_readlane_b32 s13, v253, 23
	v_readlane_b32 s14, v253, 24
	v_readlane_b32 s15, v253, 25
	v_lshlrev_b32_e32 v232, 2, v104
	v_lshlrev_b32_e32 v250, 4, v88
	v_mov_b32_e32 v233, 0
	s_and_saveexec_b64 s[54:55], s[40:41]
	global_load_ubyte v233, v[106:107], off
	s_or_b64 exec, exec, s[54:55]
	v_lshrrev_b32_e32 v251, 6, v93
	v_mul_u32_u24_e32 v251, 0x600, v251
	v_add_u32_e32 v101, v101, v251
	v_add_co_u32_e32 v102, vcc, v102, v251
	s_nop 1
	v_addc_co_u32_e32 v103, vcc, 0, v103, vcc
	s_mov_b32 s54, s74
	s_ashr_i32 s55, s74, 31
	s_lshl_b64 s[54:55], s[54:55], 13
	v_lshl_add_u64 v[218:219], v[102:103], 0, s[54:55]
	global_load_dwordx2 v[210:211], v[218:219], off sc1
	global_load_dwordx2 v[212:213], v[218:219], off offset:512 sc1
	global_load_dwordx2 v[214:215], v[218:219], off offset:1024 sc1
	global_load_dwordx2 v[216:217], v[218:219], off offset:1536 sc1
	global_load_dwordx4 v[220:223], v[116:117], off
	global_load_dwordx4 v[224:227], v[118:119], off
	s_branch .LBB0_129

; #define LND asm volatile("" : "+s"(l), "+s"(pass))
; __global__ void __launch_bounds__(256, 2) fwd_megakernel(Params P) {
;     ...
;           if (it < 2) { pass = __builtin_amdgcn_readfirstlane(it); LND; phase_inproj(P, l, pass, smem); }
;         } else {
;           if (it > 0) { pass = __builtin_amdgcn_readfirstlane(it - 1); LND; phase11(P, l, pass, smem); }
;         }
;       }
.LBB0_276:
	v_readlane_b32 s0, v252, 60
	s_mov_b64 s[40:41], 0

; DEVI void convert_chunk_fp8(const float* __restrict__ src, unsigned char* __restrict__ dst, float scale, int tid) {
;   int o = tid * 16;
;   uint4 r;
;   unsigned rr[4];
; #pragma unroll
;   for (int q = 0; q < 4; ++q) {
;     float4 a = *reinterpret_cast<const float4*>(src + o + q * 4);
;     int p = __builtin_amdgcn_cvt_pk_fp8_f32(a.x * scale, a.y * scale, 0, false);
;     p = __builtin_amdgcn_cvt_pk_fp8_f32(a.z * scale, a.w * scale, p, true);
;     rr[q] = (unsigned)p;
;   }
;   r = make_uint4(rr[0], rr[1], rr[2], rr[3]);
;   *reinterpret_cast<uint4*>(dst + o) = r;
; }
; DEVI void phase_prep(const Params& P, int l, char* smem) {
;     ...
;     } else if (id < C1) {
;       int q = id - C0;
;       convert_chunk_fp8(P.in[26] + (long)l * 16777216 + (long)q * 4096, (unsigned char*)(ws + O_UTB) + (long)q * 4096, U_SCALE, tid);
;     } else if (id < C2) {
;       int q = id - C1;
;       convert_chunk_fp8(P.in[27] + (long)l * 16777216 + (long)q * 4096, (unsigned char*)(ws + O_VTB) + (long)q * 4096, V_SCALE, tid);
.LBB0_338:
	s_andn2_b64 vcc, exec, s[6:7]
	s_cbranch_vccnz .LBB0_411
	v_readlane_b32 s90, v252, 36
	s_cmp_lg_u32 s0, 1
	s_cbranch_scc1 .Ltb_skip
	s_cmp_lg_u32 s90, 0
	s_cbranch_scc1 .Ltb_skip
	v_readlane_b32 s54, v253, 22
	v_readlane_b32 s55, v253, 23
	v_readlane_b32 s56, v253, 24
	v_readlane_b32 s57, v253, 25
	s_add_u32 s54, s54, 0x4000000
	s_addc_u32 s55, s55, 0
	s_add_u32 s56, s56, 0x4000000
	s_addc_u32 s57, s57, 0
	v_lshlrev_b32_e32 v248, 6, v93
	v_lshlrev_b32_e32 v250, 4, v93
	v_mov_b32_e32 v251, 0
	v_lshl_add_u64 v[250:251], v[64:65], 0, v[250:251]
	s_mov_b32 s1, s74
.Ltb_loop:
	s_lshl_b32 s2, s1, 14
	s_add_u32 s40, s54, s2
	s_addc_u32 s41, s55, 0
	s_add_u32 s72, s56, s2
	s_addc_u32 s73, s57, 0
	global_load_dwordx4 v[208:211], v248, s[40:41]
	global_load_dwordx4 v[212:215], v248, s[40:41] offset:16
	global_load_dwordx4 v[216:219], v248, s[40:41] offset:32
	global_load_dwordx4 v[220:223], v248, s[40:41] offset:48
	global_load_dwordx4 v[224:227], v248, s[72:73]
	global_load_dwordx4 v[228:231], v248, s[72:73] offset:16
	global_load_dwordx4 v[232:235], v248, s[72:73] offset:32
	global_load_dwordx4 v[236:239], v248, s[72:73] offset:48
	s_lshl_b32 s2, s1, 12
	s_add_u32 s76, s2, 0x2500000
	s_mov_b32 s77, 0
	v_lshl_add_u64 v[202:203], v[250:251], 0, s[76:77]
	s_add_u32 s76, s2, 0x4500000
	v_lshl_add_u64 v[204:205], v[250:251], 0, s[76:77]
	s_waitcnt vmcnt(4)
	v_mul_f32_e32 v208, 0x42800000, v208
	v_mul_f32_e32 v209, 0x42800000, v209
	v_mul_f32_e32 v210, 0x42800000, v210
	v_mul_f32_e32 v211, 0x42800000, v211
	v_mul_f32_e32 v212, 0x42800000, v212
	v_mul_f32_e32 v213, 0x42800000, v213
	v_mul_f32_e32 v214, 0x42800000, v214
	v_mul_f32_e32 v215, 0x42800000, v215
	v_mul_f32_e32 v216, 0x42800000, v216
	v_mul_f32_e32 v217, 0x42800000, v217
	v_mul_f32_e32 v218, 0x42800000, v218
	v_mul_f32_e32 v219, 0x42800000, v219
	v_mul_f32_e32 v220, 0x42800000, v220
	v_mul_f32_e32 v221, 0x42800000, v221
	v_mul_f32_e32 v222, 0x42800000, v222
	v_mul_f32_e32 v223, 0x42800000, v223
	v_mov_b32_e32 v240, v89
	v_mov_b32_e32 v241, v89
	v_mov_b32_e32 v242, v89
	v_mov_b32_e32 v243, v89
	v_cvt_pk_fp8_f32 v240, v208, v209
	v_cvt_pk_fp8_f32 v241, v212, v213
	v_cvt_pk_fp8_f32 v242, v216, v217
	v_cvt_pk_fp8_f32 v243, v220, v221
	v_cvt_pk_fp8_f32 v240, v210, v211 op_sel:[0,0,1]
	v_cvt_pk_fp8_f32 v241, v214, v215 op_sel:[0,0,1]
	v_cvt_pk_fp8_f32 v242, v218, v219 op_sel:[0,0,1]
	v_cvt_pk_fp8_f32 v243, v222, v223 op_sel:[0,0,1]
	global_store_dwordx4 v[202:203], v[240:243], off
	s_waitcnt vmcnt(1)
	v_mul_f32_e32 v224, 0x41000000, v224
	v_mul_f32_e32 v225, 0x41000000, v225
	v_mul_f32_e32 v226, 0x41000000, v226
	v_mul_f32_e32 v227, 0x41000000, v227
	v_mul_f32_e32 v228, 0x41000000, v228
	v_mul_f32_e32 v229, 0x41000000, v229
	v_mul_f32_e32 v230, 0x41000000, v230
	v_mul_f32_e32 v231, 0x41000000, v231
	v_mul_f32_e32 v232, 0x41000000, v232
	v_mul_f32_e32 v233, 0x41000000, v233
	v_mul_f32_e32 v234, 0x41000000, v234
	v_mul_f32_e32 v235, 0x41000000, v235
	v_mul_f32_e32 v236, 0x41000000, v236
	v_mul_f32_e32 v237, 0x41000000, v237
	v_mul_f32_e32 v238, 0x41000000, v238
	v_mul_f32_e32 v239, 0x41000000, v239
	v_mov_b32_e32 v244, v89
	v_mov_b32_e32 v245, v89
	v_mov_b32_e32 v246, v89
	v_mov_b32_e32 v247, v89
	v_cvt_pk_fp8_f32 v244, v224, v225
	v_cvt_pk_fp8_f32 v245, v228, v229
	v_cvt_pk_fp8_f32 v246, v232, v233
	v_cvt_pk_fp8_f32 v247, v236, v237
	v_cvt_pk_fp8_f32 v244, v226, v227 op_sel:[0,0,1]
	v_cvt_pk_fp8_f32 v245, v230, v231 op_sel:[0,0,1]
	v_cvt_pk_fp8_f32 v246, v234, v235 op_sel:[0,0,1]
	v_cvt_pk_fp8_f32 v247, v238, v239 op_sel:[0,0,1]
	global_store_dwordx4 v[204:205], v[244:247], off
	s_addk_i32 s1, 0x200
	s_cmpk_lt_u32 s1, 0x1000
	s_cbranch_scc1 .Ltb_loop
; DEVI int ltid() { int t = threadIdx.x; asm volatile("" : "+v"(t)); return t; }
; DEVI void h1_item(const Params& P, int l, int ck, int h, char* smem, int tid) {
;   const ChunkInfo ci = chunkinfo(ck);
;   const int lane = tid & 63, w = tid >> 6, fr = lane & 15, fq = lane >> 4;
;   bfu* VT = (bfu*)smem;
;   bfu* KT = VT + 128 * 72;
;   bfu* FS = KT + 128 * 72;
;   float* tots = (float*)(smem + 54272);
;   float* decl = tots + 256;
;   const int d = tid & 127, hf = tid >> 7, L = ci.L, Lh = L >> 1;
;   const float lb = ((const float*)(P.ws + O_LBS))[l * 1024 + h * 128 + d];
;   const bfu* Z = (const bfu*)(P.ws + O_Z);
;   const bfu* zfb = Z + (long)ci.lt0 * NCOL + 6 * 1024 + h * 128;
;   const bfu* zib = Z + (long)ci.lt0 * NCOL + 7 * 1024 + h * 128;
; DEVI void phase2(const Params& P, int l, int pass, char* smem) {
;   const int tid = ltid();
;   const int ntok = pass ? 8192 : 8448, base = pass ? 8448 : 0;
;   const int nck = pass ? 128 : 136;
;   const int nH = nck * 8;
;   const int total = nH + ntok / 4;
;   for (int id = blockIdx.x; id < total; id += gridDim.x) {
;     if (id < nH) h1_item(P, l, id >> 3, id & 7, smem, tid);
;     else mixab_row4(P, l, base, (id - nH) * 4, tid);
;   }
.Ltb_skip:
	s_cmp_eq_u32 s90, 0
	s_cselect_b64 s[26:27], -1, 0
	s_and_b64 s[40:41], s[26:27], exec
	s_movk_i32 s1, 0xc80
	s_cselect_b32 s2, s1, 0xc00
	s_mov_b64 s[72:73], 0x8000
	s_mov_b64 s[76:77], 0x40000
	s_mov_b64 s[56:57], 0x2000
	s_mov_b64 s[54:55], 0x1000
	v_mov_b32_e32 v91, v93
	s_cmp_ge_i32 s74, s2
	s_cbranch_scc1 .LBB0_412
	s_and_b64 s[26:27], s[26:27], exec
	s_movk_i32 s1, 0x440
	s_cselect_b32 s75, 0, 0x2100
	s_cselect_b32 s78, s1, 0x400
	s_lshl_b32 s44, s0, 2
	s_or_b32 s40, s44, 1
	s_ashr_i32 s41, s40, 31
	s_lshl_b64 s[46:47], s[40:41], 12
	s_or_b32 s40, s44, 2
	v_lshrrev_b32_e32 v0, 1, v91
	s_ashr_i32 s41, s40, 31
	v_and_b32_e32 v1, 0x7f, v91
	v_and_b32_e32 v0, 0x78, v0
	v_lshlrev_b32_e32 v100, 2, v91
	s_lshl_b64 s[48:49], s[40:41], 12
	s_or_b32 s40, s44, 3
	s_ashr_i32 s1, s0, 31
	v_lshlrev_b32_e32 v141, 1, v0
	s_movk_i32 s4, 0x8e
	v_ashrrev_i32_e32 v9, 6, v91
	v_lshlrev_b32_e32 v11, 1, v1
	v_ashrrev_i32_e32 v101, 31, v100
	s_mul_i32 s26, s0, 3
	s_ashr_i32 s41, s40, 31
	s_lshl_b64 s[52:53], s[0:1], 12
	v_and_b32_e32 v137, 15, v91
	v_mad_u32_u24 v160, v0, s4, v141
	s_movk_i32 s1, 0x80
	v_mad_u32_u24 v15, v1, s4, v11
	v_lshlrev_b32_e32 v2, 5, v9
	v_readlane_b32 s4, v254, 44
	s_ashr_i32 s27, s26, 31
	s_ashr_i32 s45, s44, 31
	s_lshl_b64 s[50:51], s[40:41], 12
	v_cmp_gt_u32_e64 s[40:41], s1, v91
	v_or_b32_e32 v3, v2, v137
	s_movk_i32 s1, 0x90
	v_lshlrev_b64 v[22:23], 2, v[100:101]
	v_readlane_b32 s5, v254, 45
	v_readlane_b32 s16, v254, 56
	v_readlane_b32 s17, v254, 57
	s_lshl_b32 s79, s0, 3
	s_lshl_b64 s[26:27], s[26:27], 12
	s_lshl_b64 s[42:43], s[44:45], 12
	v_bfe_u32 v13, v91, 4, 2
	v_mul_lo_u32 v26, v3, s1
	s_lshl_b32 s1, s0, 6
	v_lshl_add_u64 v[102:103], s[4:5], 0, v[22:23]
	v_lshl_add_u64 v[24:25], s[16:17], 0, v[22:23]
	v_readlane_b32 s4, v252, 2
	v_lshl_or_b32 v2, v13, 2, v2
	v_lshlrev_b32_e32 v9, 12, v9
	v_lshl_add_u64 v[108:109], v[24:25], 0, s[26:27]
	v_readlane_b32 s5, v252, 3
	s_add_u32 s26, s4, s52
	v_ashrrev_i32_e32 v5, 7, v91
	v_ashrrev_i32_e32 v3, 31, v2
	v_lshlrev_b32_e32 v4, 7, v137
	v_lshl_or_b32 v20, v13, 9, v9
	v_readlane_b32 s6, v254, 46
	v_readlane_b32 s7, v254, 47
	v_readlane_b32 s18, v254, 58
	v_readlane_b32 s19, v254, 59
	s_addc_u32 s27, s5, s53
	v_lshlrev_b32_e32 v88, 1, v137
	v_readlane_b32 s4, v252, 4
	v_lshl_or_b32 v139, s0, 10, v1
	v_mul_u32_u24_e32 v7, 0x48, v0
	v_lshlrev_b32_e32 v17, 5, v5
	v_mul_i32_i24_e32 v1, 0xffffff74, v1
	v_lshlrev_b32_e32 v19, 4, v13
	v_mul_u32_u24_e32 v27, 0x90, v137
	v_or_b32_e32 v6, 0x800, v4
	v_or_b32_e32 v8, 0x1000, v4
	v_or_b32_e32 v10, 0x1800, v4
	v_or_b32_e32 v12, 0x2000, v4
	v_or_b32_e32 v14, 0x2800, v4
	v_or_b32_e32 v16, 0x3000, v4
	v_or_b32_e32 v18, 0x3800, v4
	v_ashrrev_i32_e32 v21, 31, v20
	v_readlane_b32 s10, v254, 50
	v_readlane_b32 s11, v254, 51
	v_lshlrev_b64 v[104:105], 1, v[100:101]
	v_lshl_add_u64 v[116:117], s[6:7], 0, v[22:23]
	v_lshl_add_u64 v[24:25], s[18:19], 0, v[22:23]
	v_lshl_add_u64 v[126:127], s[26:27], 0, v[22:23]
	v_lshl_add_u64 v[22:23], v[84:85], 0, v[88:89]
	v_lshlrev_b64 v[2:3], 2, v[2:3]
	v_readlane_b32 s5, v252, 5
	v_mul_lo_u32 v163, v5, s37
	v_lshlrev_b32_e32 v161, 2, v137
	v_lshl_add_u64 v[106:107], v[74:75], 0, v[104:105]
	v_lshl_add_u64 v[110:111], v[108:109], 0, s[54:55]
	v_lshl_add_u64 v[112:113], v[108:109], 0, s[56:57]
	v_lshl_add_u64 v[114:115], v[76:77], 0, v[104:105]
	v_lshl_add_u64 v[118:119], v[24:25], 0, s[42:43]
	v_lshl_add_u64 v[120:121], v[24:25], 0, s[46:47]
	v_lshl_add_u64 v[122:123], v[24:25], 0, s[48:49]
	v_lshl_add_u64 v[124:125], v[24:25], 0, s[50:51]
	v_lshl_add_u64 v[128:129], v[78:79], 0, v[104:105]
	v_lshl_add_u64 v[130:131], v[20:21], 1, v[22:23]
	v_lshlrev_b32_e32 v162, 1, v7
	v_lshl_add_u64 v[132:133], s[10:11], 0, v[2:3]
	v_lshl_add_u64 v[134:135], s[4:5], 0, v[2:3]
	v_or_b32_e32 v136, 0x9000, v11
	v_add_u32_e32 v138, 0x8780, v11
	v_add_u32_e32 v164, 0x110, v163
	v_add_u32_e32 v140, 0x47f0, v15
	v_lshl_add_u32 v165, v5, 1, 2
	v_lshlrev_b32_e32 v142, 1, v0
	v_add_u32_e32 v166, v15, v17
	v_add_u32_e32 v167, v15, v1
	v_add_u32_e32 v168, v19, v26
	v_add_u32_e32 v169, v19, v27
	v_lshlrev_b32_e32 v144, 2, v4
	v_lshlrev_b32_e32 v146, 2, v6
	v_lshlrev_b32_e32 v148, 2, v8
	v_lshlrev_b32_e32 v150, 2, v10
	v_lshlrev_b32_e32 v152, 2, v12
	v_lshlrev_b32_e32 v154, 2, v14
	v_lshlrev_b32_e32 v156, 2, v16
	v_lshlrev_b32_e32 v158, 2, v18
	v_readlane_b32 s45, v252, 32
	v_readlane_b32 s8, v254, 48
	v_readlane_b32 s9, v254, 49
	v_readlane_b32 s12, v254, 52
	v_readlane_b32 s13, v254, 53
	v_readlane_b32 s14, v254, 54
	v_readlane_b32 s15, v254, 55
	s_branch .LBB0_342
